# v17 + conv_a2 A2 loop: the eight per-element mu loads (each its own vmcnt(0) round trip) fetched as two dwordx4 up front
# speedup vs baseline: 1.0204x; 1.0129x over previous
.LBB0_659:
	s_or_b64 exec, exec, s[12:13]
	s_waitcnt vmcnt(0)
	v_cvt_f32_f16_e32 v15, v4
	s_movk_i32 s1, 0xffd0
	v_readlane_b32 s8, v254, 52
	v_readlane_b32 s9, v254, 53
	v_mad_u64_u32 v[20:21], s[10:11], v13, s1, v[14:15]
	v_cmp_lt_i32_e64 s[38:39], 15, v20
	v_cmp_gt_u32_e32 vcc, 32, v20
	v_lshl_add_u64 v[20:21], v[16:17], 2, s[8:9]
	global_load_dwordx4 v[114:117], v[20:21], off
	global_load_dwordx4 v[118:121], v[20:21], off offset:16
	v_cvt_f32_f16_e32 v13, v8
	v_add_f32_e32 v13, v15, v13
	v_fma_mix_f32 v13, v13, s76, -v0 op_sel_hi:[0,0,1]
	s_waitcnt vmcnt(0)
	v_mov_b32_e32 v22, v114
	v_fma_mix_f32 v15, v22, v13, v0 op_sel_hi:[0,0,1]
	s_and_saveexec_b64 s[10:11], s[38:39]
	s_xor_b64 s[12:13], exec, s[10:11]
	s_cbranch_execz .LBB0_661
	v_mul_f32_e32 v13, 0xbfb8aa3b, v15
	v_exp_f32_e32 v13, v13
	s_nop 0
	v_add_f32_e32 v13, 1.0, v13
	v_rcp_f32_e32 v13, v13
	s_nop 0
	v_cndmask_b32_e32 v13, v13, v15, vcc

.LBB0_663:
	s_or_b64 exec, exec, s[12:13]
	v_mov_b32_e32 v15, v115
	v_cvt_f32_f16_sdwa v8, v8 dst_sel:DWORD dst_unused:UNUSED_PAD src0_sel:WORD_1
	v_cvt_f32_f16_sdwa v4, v4 dst_sel:DWORD dst_unused:UNUSED_PAD src0_sel:WORD_1
	v_add_f32_e32 v4, v4, v8
	v_fma_mix_f32 v4, v4, s76, -v0 op_sel:[0,0,1] op_sel_hi:[0,0,1]
	s_waitcnt vmcnt(0)
	v_fma_mix_f32 v4, v4, v15, v0 op_sel:[0,0,1] op_sel_hi:[0,0,1]
	s_and_saveexec_b64 s[10:11], s[38:39]
	s_xor_b64 s[12:13], exec, s[10:11]
	s_cbranch_execz .LBB0_665
	v_mul_f32_e32 v0, 0xbfb8aa3b, v4
	v_exp_f32_e32 v0, v0
	s_nop 0
	v_add_f32_e32 v0, 1.0, v0
	v_rcp_f32_e32 v0, v0
	s_nop 0
	v_cndmask_b32_e32 v0, v0, v4, vcc

.LBB0_667:
	s_or_b64 exec, exec, s[12:13]
	v_mov_b32_e32 v4, v116
	v_cvt_f32_f16_e32 v8, v9
	v_cvt_f32_f16_e32 v15, v5
	v_add_f32_e32 v8, v15, v8
	v_fma_mix_f32 v8, v8, s76, -v1 op_sel_hi:[0,0,1]
	s_waitcnt vmcnt(0)
	v_fma_mix_f32 v8, v8, v4, v1 op_sel_hi:[0,0,1]
	s_and_saveexec_b64 s[10:11], s[38:39]
	s_xor_b64 s[12:13], exec, s[10:11]
	s_cbranch_execz .LBB0_669
	v_mul_f32_e32 v4, 0xbfb8aa3b, v8
	v_exp_f32_e32 v4, v4
	s_nop 0
	v_add_f32_e32 v4, 1.0, v4
	v_rcp_f32_e32 v4, v4
	s_nop 0
	v_cndmask_b32_e32 v4, v4, v8, vcc

.LBB0_671:
	s_or_b64 exec, exec, s[12:13]
	v_mov_b32_e32 v8, v117
	v_cvt_f32_f16_sdwa v9, v9 dst_sel:DWORD dst_unused:UNUSED_PAD src0_sel:WORD_1
	v_cvt_f32_f16_sdwa v5, v5 dst_sel:DWORD dst_unused:UNUSED_PAD src0_sel:WORD_1
	v_add_f32_e32 v5, v5, v9
	v_fma_mix_f32 v5, v5, s76, -v1 op_sel:[0,0,1] op_sel_hi:[0,0,1]
	s_waitcnt vmcnt(0)
	v_fma_mix_f32 v5, v5, v8, v1 op_sel:[0,0,1] op_sel_hi:[0,0,1]
	s_and_saveexec_b64 s[10:11], s[38:39]
	s_xor_b64 s[12:13], exec, s[10:11]
	s_cbranch_execz .LBB0_673
	v_mul_f32_e32 v1, 0xbfb8aa3b, v5
	v_exp_f32_e32 v1, v1
	s_nop 0
	v_add_f32_e32 v1, 1.0, v1
	v_rcp_f32_e32 v1, v1
	s_nop 0
	v_cndmask_b32_e32 v1, v1, v5, vcc

.LBB0_675:
	s_or_b64 exec, exec, s[12:13]
	v_mov_b32_e32 v5, v118
	v_cvt_f32_f16_e32 v8, v10
	v_cvt_f32_f16_e32 v9, v6
	v_add_f32_e32 v8, v9, v8
	v_fma_mix_f32 v8, v8, s76, -v2 op_sel_hi:[0,0,1]
	s_waitcnt vmcnt(0)
	v_fma_mix_f32 v8, v8, v5, v2 op_sel_hi:[0,0,1]
	s_and_saveexec_b64 s[10:11], s[38:39]
	s_xor_b64 s[12:13], exec, s[10:11]
	s_cbranch_execz .LBB0_677
	v_mul_f32_e32 v5, 0xbfb8aa3b, v8
	v_exp_f32_e32 v5, v5
	s_nop 0
	v_add_f32_e32 v5, 1.0, v5
	v_rcp_f32_e32 v5, v5
	s_nop 0
	v_cndmask_b32_e32 v5, v5, v8, vcc

.LBB0_679:
	s_or_b64 exec, exec, s[12:13]
	v_mov_b32_e32 v8, v119
	v_cvt_f32_f16_sdwa v9, v10 dst_sel:DWORD dst_unused:UNUSED_PAD src0_sel:WORD_1
	v_cvt_f32_f16_sdwa v6, v6 dst_sel:DWORD dst_unused:UNUSED_PAD src0_sel:WORD_1
	v_add_f32_e32 v6, v6, v9
	v_fma_mix_f32 v6, v6, s76, -v2 op_sel:[0,0,1] op_sel_hi:[0,0,1]
	s_waitcnt vmcnt(0)
	v_fma_mix_f32 v6, v6, v8, v2 op_sel:[0,0,1] op_sel_hi:[0,0,1]
	s_and_saveexec_b64 s[10:11], s[38:39]
	s_xor_b64 s[12:13], exec, s[10:11]
	s_cbranch_execz .LBB0_681
	v_mul_f32_e32 v2, 0xbfb8aa3b, v6
	v_exp_f32_e32 v2, v2
	s_nop 0
	v_add_f32_e32 v2, 1.0, v2
	v_rcp_f32_e32 v2, v2
	s_nop 0
	v_cndmask_b32_e32 v2, v2, v6, vcc

.LBB0_683:
	s_or_b64 exec, exec, s[12:13]
	v_mov_b32_e32 v6, v120
	v_cvt_f32_f16_e32 v8, v11
	v_cvt_f32_f16_e32 v9, v7
	v_add_f32_e32 v8, v9, v8
	v_fma_mix_f32 v8, v8, s76, -v3 op_sel_hi:[0,0,1]
	s_waitcnt vmcnt(0)
	v_fma_mix_f32 v8, v8, v6, v3 op_sel_hi:[0,0,1]
	s_and_saveexec_b64 s[10:11], s[38:39]
	s_xor_b64 s[12:13], exec, s[10:11]
	s_cbranch_execz .LBB0_685
	v_mul_f32_e32 v6, 0xbfb8aa3b, v8
	v_exp_f32_e32 v6, v6
	s_nop 0
	v_add_f32_e32 v6, 1.0, v6
	v_rcp_f32_e32 v6, v6
	s_nop 0
	v_cndmask_b32_e32 v6, v6, v8, vcc

.LBB0_687:
	s_or_b64 exec, exec, s[12:13]
	v_mov_b32_e32 v8, v121
	v_cvt_f32_f16_sdwa v9, v11 dst_sel:DWORD dst_unused:UNUSED_PAD src0_sel:WORD_1
	v_cvt_f32_f16_sdwa v7, v7 dst_sel:DWORD dst_unused:UNUSED_PAD src0_sel:WORD_1
	v_add_f32_e32 v7, v7, v9
	v_fma_mix_f32 v7, v7, s76, -v3 op_sel:[0,0,1] op_sel_hi:[0,0,1]
	s_waitcnt vmcnt(0)
	v_fma_mix_f32 v7, v7, v8, v3 op_sel:[0,0,1] op_sel_hi:[0,0,1]
	s_and_saveexec_b64 s[10:11], s[38:39]
	s_xor_b64 s[12:13], exec, s[10:11]
	s_cbranch_execz .LBB0_689
	v_mul_f32_e32 v3, 0xbfb8aa3b, v7
	v_exp_f32_e32 v3, v3
	s_nop 0
	v_add_f32_e32 v3, 1.0, v3
	v_rcp_f32_e32 v3, v3
	s_nop 0
	v_cndmask_b32_e32 v3, v3, v7, vcc
